# skinny (meta-row) GEMM K loops: all loads of a run issued up front with counted waits (6 sites)
# speedup vs baseline: 1.0050x; 1.0011x over previous
.LBB0_377:
	v_mad_i64_i32 v[22:23], s[34:35], s44, v189, v[2:3]
	s_waitcnt lgkmcnt(0)
	s_andn2_b64 vcc, exec, s[42:43]
	global_load_dwordx4 v[40:43], v[22:23], off
	global_load_dwordx4 v[44:47], v[0:1], off
	global_load_dwordx4 v[48:51], v[22:23], off offset:64
	global_load_dwordx4 v[52:55], v[0:1], off offset:64
	global_load_dwordx4 v[56:59], v[22:23], off offset:128
	global_load_dwordx4 v[60:63], v[0:1], off offset:128
	global_load_dwordx4 v[64:67], v[22:23], off offset:192
	global_load_dwordx4 v[68:71], v[0:1], off offset:192
	global_load_dwordx4 v[72:75], v[22:23], off offset:256
	global_load_dwordx4 v[76:79], v[0:1], off offset:256
	global_load_dwordx4 v[80:83], v[22:23], off offset:320
	global_load_dwordx4 v[84:87], v[0:1], off offset:320
	global_load_dwordx4 v[88:91], v[22:23], off offset:384
	global_load_dwordx4 v[92:95], v[0:1], off offset:384
	global_load_dwordx4 v[96:99], v[22:23], off offset:448
	global_load_dwordx4 v[100:103], v[0:1], off offset:448
	global_load_dwordx4 v[104:107], v[22:23], off offset:512
	global_load_dwordx4 v[108:111], v[0:1], off offset:512
	global_load_dwordx4 v[112:115], v[22:23], off offset:576
	global_load_dwordx4 v[116:119], v[0:1], off offset:576
	global_load_dwordx4 v[120:123], v[22:23], off offset:640
	global_load_dwordx4 v[124:127], v[0:1], off offset:640
	s_waitcnt vmcnt(20)
	v_mfma_f32_16x16x32_bf16 v[8:11], v[40:43], v[44:47], 0
	s_waitcnt vmcnt(18)
	v_mfma_f32_16x16x32_bf16 v[8:11], v[48:51], v[52:55], v[8:11]
	s_waitcnt vmcnt(16)
	v_mfma_f32_16x16x32_bf16 v[8:11], v[56:59], v[60:63], v[8:11]
	s_waitcnt vmcnt(14)
	v_mfma_f32_16x16x32_bf16 v[8:11], v[64:67], v[68:71], v[8:11]
	s_waitcnt vmcnt(12)
	v_mfma_f32_16x16x32_bf16 v[8:11], v[72:75], v[76:79], v[8:11]
	s_waitcnt vmcnt(10)
	v_mfma_f32_16x16x32_bf16 v[8:11], v[80:83], v[84:87], v[8:11]
	s_waitcnt vmcnt(8)
	v_mfma_f32_16x16x32_bf16 v[8:11], v[88:91], v[92:95], v[8:11]
	s_waitcnt vmcnt(6)
	v_mfma_f32_16x16x32_bf16 v[8:11], v[96:99], v[100:103], v[8:11]
	s_waitcnt vmcnt(4)
	v_mfma_f32_16x16x32_bf16 v[8:11], v[104:107], v[108:111], v[8:11]
	s_waitcnt vmcnt(2)
	v_mfma_f32_16x16x32_bf16 v[8:11], v[112:115], v[116:119], v[8:11]
	s_waitcnt vmcnt(0)
	v_mfma_f32_16x16x32_bf16 v[8:11], v[120:123], v[124:127], v[8:11]
	v_add_u32_e32 v14, s28, v12
	s_nop 6
	ds_write_b128 v14, v[8:11]
	v_cndmask_b32_e64 v9, 0, 1, s[42:43]
	v_mov_b32_e32 v8, 0
	v_cmp_ne_u32_e64 s[40:41], 1, v9
	v_mov_b32_e32 v9, 0
	v_mov_b32_e32 v10, 0
	v_mov_b32_e32 v11, 0
	s_waitcnt lgkmcnt(0)
	s_barrier
	s_cbranch_vccnz .LBB0_379
	ds_read_b128 v[8:11], v12
	s_waitcnt lgkmcnt(0)
	v_pk_add_f32 v[14:15], v[10:11], 0 op_sel_hi:[1,0]
	v_pk_add_f32 v[16:17], v[8:9], 0 op_sel_hi:[1,0]
	ds_read_b128 v[8:11], v12 offset:1024
	s_waitcnt lgkmcnt(0)
	v_pk_add_f32 v[14:15], v[14:15], v[10:11]
	v_pk_add_f32 v[16:17], v[16:17], v[8:9]
	ds_read_b128 v[8:11], v12 offset:2048
	s_waitcnt lgkmcnt(0)
	v_pk_add_f32 v[14:15], v[14:15], v[10:11]
	v_pk_add_f32 v[16:17], v[16:17], v[8:9]
	ds_read_b128 v[8:11], v12 offset:3072
	s_waitcnt lgkmcnt(0)
	v_pk_add_f32 v[14:15], v[14:15], v[10:11]
	v_pk_add_f32 v[16:17], v[16:17], v[8:9]
	ds_read_b128 v[8:11], v12 offset:4096
	s_waitcnt lgkmcnt(0)
	v_pk_add_f32 v[14:15], v[14:15], v[10:11]
	v_pk_add_f32 v[16:17], v[16:17], v[8:9]
	ds_read_b128 v[8:11], v12 offset:5120
	s_waitcnt lgkmcnt(0)
	v_pk_add_f32 v[14:15], v[14:15], v[10:11]
	v_pk_add_f32 v[16:17], v[16:17], v[8:9]
	ds_read_b128 v[8:11], v12 offset:6144
	s_waitcnt lgkmcnt(0)
	v_pk_add_f32 v[14:15], v[14:15], v[10:11]
	v_pk_add_f32 v[16:17], v[16:17], v[8:9]
	ds_read_b128 v[8:11], v12 offset:7168
	s_waitcnt lgkmcnt(0)
	v_pk_add_f32 v[10:11], v[14:15], v[10:11]
	v_pk_add_f32 v[8:9], v[16:17], v[8:9]
	v_pk_mul_f32 v[10:11], v[10:11], 0.5 op_sel_hi:[1,0]
	v_pk_mul_f32 v[8:9], v[8:9], 0.5 op_sel_hi:[1,0]

.LBB0_546:
	s_cmpk_lt_i32 s36, 0xe1
	s_cselect_b64 s[64:65], -1, 0
	s_add_i32 s4, s33, 0xfffff1f0
	s_cmpk_gt_i32 s36, 0xe0
	s_cselect_b32 s66, s4, s33
	s_cselect_b32 s5, s46, s54
	s_cselect_b32 s34, s55, s53
	s_ashr_i32 s67, s66, 31
	s_lshl_b64 s[28:29], s[66:67], 11
	s_add_u32 s4, s34, s28
	s_addc_u32 s5, s5, s29
	s_add_u32 s28, s4, s2
	s_addc_u32 s29, s5, s3
	v_mov_b32_e32 v23, v145
	v_lshl_add_u64 v[0:1], s[28:29], 0, v[22:23]
	v_mov_b32_e32 v25, v145
	v_lshl_add_u64 v[30:31], v[0:1], 0, v[24:25]
	s_andn2_b64 vcc, exec, s[42:43]
	v_mov_b32_e32 v32, 0
	v_mov_b32_e32 v33, 0
	global_load_dwordx4 v[48:51], v[30:31], off
	global_load_dwordx4 v[52:55], v[12:13], off
	global_load_dwordx4 v[56:59], v[30:31], off offset:64
	global_load_dwordx4 v[60:63], v[12:13], off offset:64
	global_load_dwordx4 v[64:67], v[30:31], off offset:128
	global_load_dwordx4 v[68:71], v[12:13], off offset:128
	global_load_dwordx4 v[72:75], v[30:31], off offset:192
	global_load_dwordx4 v[76:79], v[12:13], off offset:192
	v_mov_b32_e32 v30, 0
	v_mov_b32_e32 v31, 0
	s_waitcnt vmcnt(6)
	v_mfma_f32_16x16x32_bf16 v[0:3], v[48:51], v[52:55], 0
	s_waitcnt vmcnt(4)
	v_mfma_f32_16x16x32_bf16 v[0:3], v[56:59], v[60:63], v[0:3]
	s_waitcnt vmcnt(2)
	v_mfma_f32_16x16x32_bf16 v[0:3], v[64:67], v[68:71], v[0:3]
	s_waitcnt vmcnt(0)
	v_mfma_f32_16x16x32_bf16 v[0:3], v[72:75], v[76:79], v[0:3]
	v_add_u32_e32 v4, s30, v38
	s_nop 6
	ds_write_b128 v4, v[0:3]
	v_cndmask_b32_e64 v0, 0, 1, s[42:43]
	v_cmp_ne_u32_e64 s[40:41], 1, v0
	s_waitcnt lgkmcnt(0)
	s_barrier
	s_cbranch_vccnz .LBB0_548
	ds_read_b128 v[0:3], v38
	s_waitcnt lgkmcnt(0)
	v_pk_add_f32 v[4:5], v[2:3], 0 op_sel_hi:[1,0]
	v_pk_add_f32 v[6:7], v[0:1], 0 op_sel_hi:[1,0]
	ds_read_b128 v[0:3], v38 offset:1024
	s_waitcnt lgkmcnt(0)
	v_pk_add_f32 v[4:5], v[4:5], v[2:3]
	v_pk_add_f32 v[6:7], v[6:7], v[0:1]
	ds_read_b128 v[0:3], v38 offset:2048
	s_waitcnt lgkmcnt(0)
	v_pk_add_f32 v[4:5], v[4:5], v[2:3]
	v_pk_add_f32 v[6:7], v[6:7], v[0:1]
	ds_read_b128 v[0:3], v38 offset:3072
	s_waitcnt lgkmcnt(0)
	v_pk_add_f32 v[4:5], v[4:5], v[2:3]
	v_pk_add_f32 v[6:7], v[6:7], v[0:1]
	ds_read_b128 v[0:3], v38 offset:4096
	s_waitcnt lgkmcnt(0)
	v_pk_add_f32 v[4:5], v[4:5], v[2:3]
	v_pk_add_f32 v[6:7], v[6:7], v[0:1]
	ds_read_b128 v[0:3], v38 offset:5120
	s_waitcnt lgkmcnt(0)
	v_pk_add_f32 v[4:5], v[4:5], v[2:3]
	v_pk_add_f32 v[6:7], v[6:7], v[0:1]
	ds_read_b128 v[0:3], v38 offset:6144
	s_waitcnt lgkmcnt(0)
	v_pk_add_f32 v[4:5], v[4:5], v[2:3]
	v_pk_add_f32 v[6:7], v[6:7], v[0:1]
	ds_read_b128 v[0:3], v38 offset:7168
	s_waitcnt lgkmcnt(0)
	v_pk_add_f32 v[32:33], v[4:5], v[2:3]
	v_pk_add_f32 v[30:31], v[6:7], v[0:1]

.LBB0_983:
	s_waitcnt lgkmcnt(0)
	v_add_u32_e32 v11, s28, v10
	s_andn2_b64 vcc, exec, s[44:45]
	global_load_dwordx4 v[40:43], v[4:5], off
	global_load_dwordx4 v[44:47], v[0:1], off
	global_load_dwordx4 v[48:51], v[4:5], off offset:64
	global_load_dwordx4 v[52:55], v[0:1], off offset:64
	s_waitcnt vmcnt(2)
	v_mfma_f32_16x16x32_bf16 v[6:9], v[40:43], v[44:47], 0
	s_waitcnt vmcnt(0)
	v_mfma_f32_16x16x32_bf16 v[6:9], v[48:51], v[52:55], v[6:9]
	s_nop 7
	ds_write_b128 v11, v[6:9]
	v_cndmask_b32_e64 v6, 0, 1, s[44:45]
	v_mov_b32_e32 v8, 0
	v_cmp_ne_u32_e64 s[40:41], 1, v6
	v_mov_b32_e32 v9, 0
	v_mov_b32_e32 v6, 0
	v_mov_b32_e32 v7, 0
	s_waitcnt lgkmcnt(0)
	s_barrier
	s_cbranch_vccnz .LBB0_985
	ds_read_b128 v[6:9], v10
	s_waitcnt lgkmcnt(0)
	v_pk_add_f32 v[12:13], v[8:9], 0 op_sel_hi:[1,0]
	v_pk_add_f32 v[14:15], v[6:7], 0 op_sel_hi:[1,0]
	ds_read_b128 v[6:9], v10 offset:1024
	s_waitcnt lgkmcnt(0)
	v_pk_add_f32 v[12:13], v[12:13], v[8:9]
	v_pk_add_f32 v[14:15], v[14:15], v[6:7]
	ds_read_b128 v[6:9], v10 offset:2048
	s_waitcnt lgkmcnt(0)
	v_pk_add_f32 v[12:13], v[12:13], v[8:9]
	v_pk_add_f32 v[14:15], v[14:15], v[6:7]
	ds_read_b128 v[6:9], v10 offset:3072
	s_waitcnt lgkmcnt(0)
	v_pk_add_f32 v[12:13], v[12:13], v[8:9]
	v_pk_add_f32 v[14:15], v[14:15], v[6:7]
	ds_read_b128 v[6:9], v10 offset:4096
	s_waitcnt lgkmcnt(0)
	v_pk_add_f32 v[12:13], v[12:13], v[8:9]
	v_pk_add_f32 v[14:15], v[14:15], v[6:7]
	ds_read_b128 v[6:9], v10 offset:5120
	s_waitcnt lgkmcnt(0)
	v_pk_add_f32 v[12:13], v[12:13], v[8:9]
	v_pk_add_f32 v[14:15], v[14:15], v[6:7]
	ds_read_b128 v[6:9], v10 offset:6144
	s_waitcnt lgkmcnt(0)
	v_pk_add_f32 v[8:9], v[12:13], v[8:9]
	v_pk_add_f32 v[16:17], v[14:15], v[6:7]
	ds_read_b128 v[12:15], v10 offset:7168
	s_waitcnt lgkmcnt(0)
	v_pk_add_f32 v[6:7], v[8:9], v[14:15]
	v_pk_add_f32 v[8:9], v[16:17], v[12:13]

.LBB0_1183:
	s_ashr_i32 s47, s46, 31
	s_lshl_b64 s[4:5], s[46:47], 11
	v_lshl_add_u64 v[22:23], v[2:3], 0, s[4:5]
	s_waitcnt lgkmcnt(0)
	s_andn2_b64 vcc, exec, s[44:45]
	global_load_dwordx4 v[40:43], v[22:23], off
	global_load_dwordx4 v[44:47], v[0:1], off
	global_load_dwordx4 v[48:51], v[22:23], off offset:64
	global_load_dwordx4 v[52:55], v[0:1], off offset:64
	global_load_dwordx4 v[56:59], v[22:23], off offset:128
	global_load_dwordx4 v[60:63], v[0:1], off offset:128
	global_load_dwordx4 v[64:67], v[22:23], off offset:192
	global_load_dwordx4 v[68:71], v[0:1], off offset:192
	s_waitcnt vmcnt(6)
	v_mfma_f32_16x16x32_bf16 v[8:11], v[40:43], v[44:47], 0
	s_waitcnt vmcnt(4)
	v_mfma_f32_16x16x32_bf16 v[8:11], v[48:51], v[52:55], v[8:11]
	s_waitcnt vmcnt(2)
	v_mfma_f32_16x16x32_bf16 v[8:11], v[56:59], v[60:63], v[8:11]
	s_waitcnt vmcnt(0)
	v_mfma_f32_16x16x32_bf16 v[8:11], v[64:67], v[68:71], v[8:11]
	v_add_u32_e32 v14, s28, v12
	s_nop 6
	ds_write_b128 v14, v[8:11]
	v_cndmask_b32_e64 v9, 0, 1, s[44:45]
	v_mov_b32_e32 v8, 0
	v_cmp_ne_u32_e64 s[40:41], 1, v9
	v_mov_b32_e32 v9, 0
	v_mov_b32_e32 v10, 0
	v_mov_b32_e32 v11, 0
	s_waitcnt lgkmcnt(0)
	s_barrier
	s_cbranch_vccnz .LBB0_1185
	ds_read_b128 v[8:11], v12
	s_waitcnt lgkmcnt(0)
	v_pk_add_f32 v[14:15], v[10:11], 0 op_sel_hi:[1,0]
	v_pk_add_f32 v[16:17], v[8:9], 0 op_sel_hi:[1,0]
	ds_read_b128 v[8:11], v12 offset:1024
	s_waitcnt lgkmcnt(0)
	v_pk_add_f32 v[14:15], v[14:15], v[10:11]
	v_pk_add_f32 v[16:17], v[16:17], v[8:9]
	ds_read_b128 v[8:11], v12 offset:2048
	s_waitcnt lgkmcnt(0)
	v_pk_add_f32 v[14:15], v[14:15], v[10:11]
	v_pk_add_f32 v[16:17], v[16:17], v[8:9]
	ds_read_b128 v[8:11], v12 offset:3072
	s_waitcnt lgkmcnt(0)
	v_pk_add_f32 v[14:15], v[14:15], v[10:11]
	v_pk_add_f32 v[16:17], v[16:17], v[8:9]
	ds_read_b128 v[8:11], v12 offset:4096
	s_waitcnt lgkmcnt(0)
	v_pk_add_f32 v[14:15], v[14:15], v[10:11]
	v_pk_add_f32 v[16:17], v[16:17], v[8:9]
	ds_read_b128 v[8:11], v12 offset:5120
	s_waitcnt lgkmcnt(0)
	v_pk_add_f32 v[14:15], v[14:15], v[10:11]
	v_pk_add_f32 v[16:17], v[16:17], v[8:9]
	ds_read_b128 v[8:11], v12 offset:6144
	s_waitcnt lgkmcnt(0)
	v_pk_add_f32 v[14:15], v[14:15], v[10:11]
	v_pk_add_f32 v[16:17], v[16:17], v[8:9]
	ds_read_b128 v[8:11], v12 offset:7168
	s_waitcnt lgkmcnt(0)
	v_pk_add_f32 v[10:11], v[14:15], v[10:11]
	v_pk_add_f32 v[8:9], v[16:17], v[8:9]

.LBB0_1291:
	s_waitcnt lgkmcnt(0)
	s_andn2_b64 vcc, exec, s[44:45]
	global_load_dwordx4 v[40:43], v[6:7], off offset:-128
	global_load_dwordx4 v[44:47], v[0:1], off
	global_load_dwordx4 v[48:51], v[6:7], off offset:-64
	global_load_dwordx4 v[52:55], v[0:1], off offset:64
	global_load_dwordx4 v[56:59], v[6:7], off
	global_load_dwordx4 v[60:63], v[0:1], off offset:128
	global_load_dwordx4 v[64:67], v[6:7], off offset:64
	global_load_dwordx4 v[68:71], v[0:1], off offset:192
	s_waitcnt vmcnt(6)
	v_mfma_f32_16x16x32_bf16 v[8:11], v[40:43], v[44:47], 0
	s_waitcnt vmcnt(4)
	v_mfma_f32_16x16x32_bf16 v[8:11], v[48:51], v[52:55], v[8:11]
	s_waitcnt vmcnt(2)
	v_mfma_f32_16x16x32_bf16 v[8:11], v[56:59], v[60:63], v[8:11]
	s_waitcnt vmcnt(0)
	v_mfma_f32_16x16x32_bf16 v[8:11], v[64:67], v[68:71], v[8:11]
	v_add_u32_e32 v12, s28, v16
	s_nop 6
	ds_write_b128 v12, v[8:11]
	v_cndmask_b32_e64 v8, 0, 1, s[44:45]
	v_mov_b32_e32 v10, 0
	v_cmp_ne_u32_e64 s[40:41], 1, v8
	v_mov_b32_e32 v11, 0
	v_mov_b32_e32 v8, 0
	v_mov_b32_e32 v9, 0
	s_waitcnt lgkmcnt(0)
	s_barrier
	s_cbranch_vccnz .LBB0_1293
	ds_read_b128 v[8:11], v16
	s_waitcnt lgkmcnt(0)
	v_pk_add_f32 v[12:13], v[10:11], 0 op_sel_hi:[1,0]
	v_pk_add_f32 v[14:15], v[8:9], 0 op_sel_hi:[1,0]
	ds_read_b128 v[8:11], v16 offset:1024
	s_waitcnt lgkmcnt(0)
	v_pk_add_f32 v[12:13], v[12:13], v[10:11]
	v_pk_add_f32 v[14:15], v[14:15], v[8:9]
	ds_read_b128 v[8:11], v16 offset:2048
	s_waitcnt lgkmcnt(0)
	v_pk_add_f32 v[12:13], v[12:13], v[10:11]
	v_pk_add_f32 v[14:15], v[14:15], v[8:9]
	ds_read_b128 v[8:11], v16 offset:3072
	s_waitcnt lgkmcnt(0)
	v_pk_add_f32 v[12:13], v[12:13], v[10:11]
	v_pk_add_f32 v[14:15], v[14:15], v[8:9]
	ds_read_b128 v[8:11], v16 offset:4096
	s_waitcnt lgkmcnt(0)
	v_pk_add_f32 v[12:13], v[12:13], v[10:11]
	v_pk_add_f32 v[14:15], v[14:15], v[8:9]
	ds_read_b128 v[8:11], v16 offset:5120
	s_waitcnt lgkmcnt(0)
	v_pk_add_f32 v[12:13], v[12:13], v[10:11]
	v_pk_add_f32 v[14:15], v[14:15], v[8:9]
	ds_read_b128 v[8:11], v16 offset:6144
	s_waitcnt lgkmcnt(0)
	v_pk_add_f32 v[18:19], v[12:13], v[10:11]
	ds_read_b128 v[10:13], v16 offset:7168
	v_pk_add_f32 v[14:15], v[14:15], v[8:9]
	s_waitcnt lgkmcnt(0)
	v_pk_add_f32 v[8:9], v[18:19], v[12:13]
	v_pk_add_f32 v[10:11], v[14:15], v[10:11]

.LBB0_1371:
	v_mad_i64_i32 v[22:23], s[4:5], s46, v189, v[2:3]
	s_waitcnt lgkmcnt(0)
	s_andn2_b64 vcc, exec, s[44:45]
	global_load_dwordx4 v[40:43], v[22:23], off
	global_load_dwordx4 v[44:47], v[0:1], off
	global_load_dwordx4 v[48:51], v[22:23], off offset:64
	global_load_dwordx4 v[52:55], v[0:1], off offset:64
	global_load_dwordx4 v[56:59], v[22:23], off offset:128
	global_load_dwordx4 v[60:63], v[0:1], off offset:128
	global_load_dwordx4 v[64:67], v[22:23], off offset:192
	global_load_dwordx4 v[68:71], v[0:1], off offset:192
	global_load_dwordx4 v[72:75], v[22:23], off offset:256
	global_load_dwordx4 v[76:79], v[0:1], off offset:256
	global_load_dwordx4 v[80:83], v[22:23], off offset:320
	global_load_dwordx4 v[84:87], v[0:1], off offset:320
	global_load_dwordx4 v[88:91], v[22:23], off offset:384
	global_load_dwordx4 v[92:95], v[0:1], off offset:384
	global_load_dwordx4 v[96:99], v[22:23], off offset:448
	global_load_dwordx4 v[100:103], v[0:1], off offset:448
	global_load_dwordx4 v[104:107], v[22:23], off offset:512
	global_load_dwordx4 v[108:111], v[0:1], off offset:512
	global_load_dwordx4 v[112:115], v[22:23], off offset:576
	global_load_dwordx4 v[116:119], v[0:1], off offset:576
	global_load_dwordx4 v[120:123], v[22:23], off offset:640
	global_load_dwordx4 v[124:127], v[0:1], off offset:640
	s_waitcnt vmcnt(20)
	v_mfma_f32_16x16x32_bf16 v[8:11], v[40:43], v[44:47], 0
	s_waitcnt vmcnt(18)
	v_mfma_f32_16x16x32_bf16 v[8:11], v[48:51], v[52:55], v[8:11]
	s_waitcnt vmcnt(16)
	v_mfma_f32_16x16x32_bf16 v[8:11], v[56:59], v[60:63], v[8:11]
	s_waitcnt vmcnt(14)
	v_mfma_f32_16x16x32_bf16 v[8:11], v[64:67], v[68:71], v[8:11]
	s_waitcnt vmcnt(12)
	v_mfma_f32_16x16x32_bf16 v[8:11], v[72:75], v[76:79], v[8:11]
	s_waitcnt vmcnt(10)
	v_mfma_f32_16x16x32_bf16 v[8:11], v[80:83], v[84:87], v[8:11]
	s_waitcnt vmcnt(8)
	v_mfma_f32_16x16x32_bf16 v[8:11], v[88:91], v[92:95], v[8:11]
	s_waitcnt vmcnt(6)
	v_mfma_f32_16x16x32_bf16 v[8:11], v[96:99], v[100:103], v[8:11]
	s_waitcnt vmcnt(4)
	v_mfma_f32_16x16x32_bf16 v[8:11], v[104:107], v[108:111], v[8:11]
	s_waitcnt vmcnt(2)
	v_mfma_f32_16x16x32_bf16 v[8:11], v[112:115], v[116:119], v[8:11]
	s_waitcnt vmcnt(0)
	v_mfma_f32_16x16x32_bf16 v[8:11], v[120:123], v[124:127], v[8:11]
	v_add_u32_e32 v14, s28, v12
	s_nop 6
	ds_write_b128 v14, v[8:11]
	v_cndmask_b32_e64 v9, 0, 1, s[44:45]
	v_mov_b32_e32 v8, 0
	v_cmp_ne_u32_e64 s[40:41], 1, v9
	v_mov_b32_e32 v9, 0
	v_mov_b32_e32 v10, 0
	v_mov_b32_e32 v11, 0
	s_waitcnt lgkmcnt(0)
	s_barrier
	s_cbranch_vccnz .LBB0_1373
	ds_read_b128 v[8:11], v12
	s_waitcnt lgkmcnt(0)
	v_pk_add_f32 v[14:15], v[10:11], 0 op_sel_hi:[1,0]
	v_pk_add_f32 v[16:17], v[8:9], 0 op_sel_hi:[1,0]
	ds_read_b128 v[8:11], v12 offset:1024
	s_waitcnt lgkmcnt(0)
	v_pk_add_f32 v[14:15], v[14:15], v[10:11]
	v_pk_add_f32 v[16:17], v[16:17], v[8:9]
	ds_read_b128 v[8:11], v12 offset:2048
	s_waitcnt lgkmcnt(0)
	v_pk_add_f32 v[14:15], v[14:15], v[10:11]
	v_pk_add_f32 v[16:17], v[16:17], v[8:9]
	ds_read_b128 v[8:11], v12 offset:3072
	s_waitcnt lgkmcnt(0)
	v_pk_add_f32 v[14:15], v[14:15], v[10:11]
	v_pk_add_f32 v[16:17], v[16:17], v[8:9]
	ds_read_b128 v[8:11], v12 offset:4096
	s_waitcnt lgkmcnt(0)
	v_pk_add_f32 v[14:15], v[14:15], v[10:11]
	v_pk_add_f32 v[16:17], v[16:17], v[8:9]
	ds_read_b128 v[8:11], v12 offset:5120
	s_waitcnt lgkmcnt(0)
	v_pk_add_f32 v[14:15], v[14:15], v[10:11]
	v_pk_add_f32 v[16:17], v[16:17], v[8:9]
	ds_read_b128 v[8:11], v12 offset:6144
	s_waitcnt lgkmcnt(0)
	v_pk_add_f32 v[14:15], v[14:15], v[10:11]
	v_pk_add_f32 v[16:17], v[16:17], v[8:9]
	ds_read_b128 v[8:11], v12 offset:7168
	s_waitcnt lgkmcnt(0)
	v_pk_add_f32 v[10:11], v[14:15], v[10:11]
	v_pk_add_f32 v[8:9], v[16:17], v[8:9]
	v_pk_mul_f32 v[10:11], v[10:11], 0.5 op_sel_hi:[1,0]
	v_pk_mul_f32 v[8:9], v[8:9], 0.5 op_sel_hi:[1,0]
